# P3 attention combine: sub-layer-norm gain loaded once into free VGPRs; per-step reload + vmcnt(0) store drain removed (15 per wave)
# speedup vs baseline: 1.0008x; 1.0008x over previous
; __device__ __forceinline__ unsigned pk2(float lo, float hi) { return pg8::cvt_pk_bf16(lo, hi); }
; __device__ __forceinline__ float bf_lo(unsigned w) { return __uint_as_float(w << 16); }
; __device__ __forceinline__ float bf_hi(unsigned w) { return __uint_as_float(w & 0xffff0000u); }
; __global__ void __launch_bounds__(512, 2) fwd_mega(Params P_by_kernarg) {
;     ...
;         for (int row = gw; row < MX; row += 4 * NGW) {
;             u32x4 av[4][4], bv[4][4];
; #pragma unroll
;             for (int q = 0; q < 4; ++q) { const int rq = (row + q * NGW < MX) ? row + q * NGW : row;
; #pragma unroll
;                 for (int j = 0; j < 4; ++j) { const int col = (lane + 64 * j) * 8;
;                     av[q][j] = *(const u32x4*)(Opart + (size_t)rq * 2048 + col); bv[q][j] = *(const u32x4*)(Opart + (size_t)MX * 2048 + (size_t)rq * 2048 + col); } }
; #pragma unroll
;             for (int q = 0; q < 4; ++q) { const int rq = row + q * NGW; if (rq < MX) {
; #pragma unroll
;             for (int j = 0; j < 4; ++j) { const int col = (lane + 64 * j) * 8;
;                 const u32x4 a = av[q][j], bq = bv[q][j];
;                 float d[8]; d[0] = bf_lo(a.x) - lam * bf_lo(bq.x); d[1] = bf_hi(a.x) - lam * bf_hi(bq.x); d[2] = bf_lo(a.y) - lam * bf_lo(bq.y); d[3] = bf_hi(a.y) - lam * bf_hi(bq.y);
;                 d[4] = bf_lo(a.z) - lam * bf_lo(bq.z); d[5] = bf_hi(a.z) - lam * bf_hi(bq.z); d[6] = bf_lo(a.w) - lam * bf_lo(bq.w); d[7] = bf_hi(a.w) - lam * bf_hi(bq.w);
;                 float ss = 0.f;
; #pragma unroll
;                 for (int e = 0; e < 8; ++e) ss += d[e] * d[e];
;                 ss += __shfl_xor(ss, 1); ss += __shfl_xor(ss, 2); ss += __shfl_xor(ss, 4); ss += __shfl_xor(ss, 8); ss += __shfl_xor(ss, 16);
;                 const float rs = rsqrtf(ss * (1.f / 256.f) + EPS) * 0.8f;
;                 const f32x4 g0 = *(const f32x4*)(KA->in[8] + (col & 255)), g1 = *(const f32x4*)(KA->in[8] + (col & 255) + 4);
;                 u32x4 w; w.x = pk2(d[0] * rs * g0[0], d[1] * rs * g0[1]); w.y = pk2(d[2] * rs * g0[2], d[3] * rs * g0[3]); w.z = pk2(d[4] * rs * g1[0], d[5] * rs * g1[1]); w.w = pk2(d[6] * rs * g1[2], d[7] * rs * g1[3]);
;                 *(u32x4*)(Cat + (size_t)rq * DM + col) = w; } } }
.LBB0_611:
	v_lshl_add_u64 v[2:3], s[16:17], 0, v[126:127]
	v_add_co_u32_e32 v10, vcc, s21, v2
	s_add_i32 s2, s20, s55
	s_nop 0
	v_addc_co_u32_e32 v11, vcc, 0, v3, vcc
	v_add_co_u32_e32 v12, vcc, s52, v2
	s_cmpk_lt_i32 s2, 0x2000
	s_nop 0
	v_addc_co_u32_e32 v13, vcc, 0, v3, vcc
	global_load_dwordx4 v[2:5], v[12:13], off
	global_load_dwordx4 v[6:9], v[10:11], off
	global_load_dwordx4 v[114:117], v[10:11], off offset:1024
	global_load_dwordx4 v[118:121], v[12:13], off offset:1024
	global_load_dwordx4 v[144:147], v[128:129], off offset:16
	global_load_dwordx4 v[148:151], v[128:129], off
	global_load_dwordx4 v[204:207], v[128:129], off offset:16
	global_load_dwordx4 v[200:203], v[128:129], off
	s_cselect_b32 s42, s2, s55
	s_ashr_i32 s43, s42, 31
	s_lshl_b64 s[42:43], s[42:43], 12
	global_load_dwordx4 v[98:101], v[10:11], off offset:3072
	global_load_dwordx4 v[106:109], v[10:11], off offset:2048
	global_load_dwordx4 v[102:105], v[12:13], off offset:3072
	global_load_dwordx4 v[110:113], v[12:13], off offset:2048
	v_lshl_add_u64 v[10:11], v[130:131], 0, s[42:43]
	v_lshl_add_u64 v[12:13], v[132:133], 0, s[42:43]
	global_load_dwordx4 v[90:93], v[10:11], off
	global_load_dwordx4 v[82:85], v[10:11], off offset:1024
	global_load_dwordx4 v[94:97], v[12:13], off
	global_load_dwordx4 v[86:89], v[12:13], off offset:1024
	global_load_dwordx4 v[74:77], v[10:11], off offset:2048
	global_load_dwordx4 v[66:69], v[10:11], off offset:3072
	global_load_dwordx4 v[78:81], v[12:13], off offset:2048
	global_load_dwordx4 v[70:73], v[12:13], off offset:3072
	s_add_i32 s46, s9, s55
	s_cmpk_lt_i32 s46, 0x2000
	s_cselect_b64 s[48:49], -1, 0
	s_and_b64 s[42:43], s[48:49], exec
	s_cselect_b32 s44, s46, s55
	s_ashr_i32 s45, s44, 31
	s_add_i32 s42, s19, s55
	s_lshl_b64 s[44:45], s[44:45], 12
	s_cmpk_lt_i32 s42, 0x2000
	v_lshl_add_u64 v[10:11], v[130:131], 0, s[44:45]
	global_load_dwordx4 v[58:61], v[10:11], off
	global_load_dwordx4 v[50:53], v[10:11], off offset:1024
	s_waitcnt vmcnt(19)
	v_and_b32_e32 v18, 0xffff0000, v2
	s_waitcnt vmcnt(18)
	v_and_b32_e32 v19, 0xffff0000, v6
	v_lshlrev_b32_e32 v16, 16, v2
	v_lshlrev_b32_e32 v17, 16, v6
	v_lshlrev_b32_e32 v2, 16, v3
	v_and_b32_e32 v3, 0xffff0000, v3
	v_lshlrev_b32_e32 v6, 16, v7
	v_and_b32_e32 v7, 0xffff0000, v7
	v_lshlrev_b32_e32 v12, 16, v4
	v_and_b32_e32 v13, 0xffff0000, v4
	v_lshlrev_b32_e32 v14, 16, v8
	v_and_b32_e32 v15, 0xffff0000, v8
	v_lshlrev_b32_e32 v4, 16, v5
	v_and_b32_e32 v5, 0xffff0000, v5
	v_lshlrev_b32_e32 v8, 16, v9
	v_and_b32_e32 v9, 0xffff0000, v9
	v_fma_f32 v156, -v122, v19, v18
	v_fma_f32 v143, -v122, v17, v16
	v_pk_fma_f32 v[136:137], v[122:123], v[6:7], v[2:3] neg_lo:[1,0,0] neg_hi:[1,0,0]
	v_pk_fma_f32 v[154:155], v[122:123], v[8:9], v[4:5] neg_lo:[1,0,0] neg_hi:[1,0,0]
	v_mul_f32_e32 v8, v156, v156
	v_pk_mul_f32 v[2:3], v[136:137], v[136:137]
	v_fmac_f32_e32 v8, v143, v143
	v_pk_fma_f32 v[152:153], v[122:123], v[14:15], v[12:13] neg_lo:[1,0,0] neg_hi:[1,0,0]
	v_add_f32_e32 v2, v8, v2
	v_pk_mul_f32 v[4:5], v[152:153], v[152:153]
	v_add_f32_e32 v2, v2, v3
	v_add_f32_e32 v2, v2, v4
	v_pk_mul_f32 v[6:7], v[154:155], v[154:155]
	v_add_f32_e32 v2, v2, v5
	v_add_f32_e32 v2, v2, v6
	v_add_f32_e32 v4, v2, v7
	ds_bpermute_b32 v5, v125, v4
	v_lshl_add_u64 v[2:3], v[132:133], 0, s[44:45]
	s_cselect_b64 s[44:45], -1, 0
	s_and_b64 s[50:51], s[44:45], exec
	s_cselect_b32 s50, s42, s55
	s_waitcnt lgkmcnt(0)
	v_add_f32_e32 v4, v4, v5
	ds_bpermute_b32 v5, v138, v4
	s_ashr_i32 s51, s50, 31
	s_lshl_b64 s[50:51], s[50:51], 12
	global_load_dwordx4 v[62:65], v[2:3], off
	global_load_dwordx4 v[54:57], v[2:3], off offset:1024
	global_load_dwordx4 v[42:45], v[10:11], off offset:2048
	global_load_dwordx4 v[34:37], v[10:11], off offset:3072
	global_load_dwordx4 v[46:49], v[2:3], off offset:2048
	global_load_dwordx4 v[38:41], v[2:3], off offset:3072
	s_waitcnt lgkmcnt(0)
	v_add_f32_e32 v4, v4, v5
	ds_bpermute_b32 v5, v139, v4
	v_lshl_add_u64 v[2:3], v[130:131], 0, s[50:51]
	v_lshl_add_u64 v[6:7], v[132:133], 0, s[50:51]
	global_load_dwordx4 v[26:29], v[2:3], off
	global_load_dwordx4 v[18:21], v[2:3], off offset:1024
	global_load_dwordx4 v[30:33], v[6:7], off
	global_load_dwordx4 v[22:25], v[6:7], off offset:1024
	s_cmpk_gt_i32 s2, 0x1fff
	s_waitcnt lgkmcnt(0)
	v_add_f32_e32 v4, v4, v5
	ds_bpermute_b32 v5, v140, v4
	s_waitcnt lgkmcnt(0)
	v_add_f32_e32 v4, v4, v5
	ds_bpermute_b32 v5, v141, v4
	s_waitcnt lgkmcnt(0)
	v_add_f32_e32 v4, v4, v5
	v_fmamk_f32 v4, v4, 0x3b800000, v142
	v_mul_f32_e32 v5, 0x4b800000, v4
	v_cmp_gt_f32_e32 vcc, s53, v4
	s_nop 1
	v_cndmask_b32_e32 v4, v4, v5, vcc
	v_rsq_f32_e32 v157, v4
	global_load_dwordx4 v[10:13], v[2:3], off offset:2048
	s_nop 0
	global_load_dwordx4 v[2:5], v[2:3], off offset:3072
	s_nop 0
	global_load_dwordx4 v[14:17], v[6:7], off offset:2048
	s_nop 0
	global_load_dwordx4 v[6:9], v[6:7], off offset:3072
	v_mul_f32_e32 v158, 0x45800000, v157
	v_cndmask_b32_e32 v157, v157, v158, vcc
	v_mul_f32_e32 v157, 0x3f4ccccd, v157
	v_mul_f32_e32 v136, v136, v157
	v_mul_f32_e32 v143, v143, v157
	v_mul_f32_e32 v156, v156, v157
	v_mul_f32_e32 v137, v137, v157
	v_mul_f32_e32 v152, v152, v157
	v_mul_f32_e32 v153, v153, v157
	s_waitcnt vmcnt(28)
	v_mul_f32_e32 v136, v150, v136
	v_mul_f32_e32 v143, v148, v143
	v_mul_f32_e32 v148, v149, v156
	v_mul_f32_e32 v137, v151, v137
	v_mul_f32_e32 v149, v144, v152
	v_mul_f32_e32 v150, v145, v153
	v_cvt_pk_bf16_f32 v144, v143, v148
	v_cvt_pk_bf16_f32 v145, v136, v137
	v_mul_f32_e32 v136, v155, v157
	v_mul_f32_e32 v154, v154, v157
	v_mul_f32_e32 v136, v147, v136
	v_mul_f32_e32 v151, v146, v154
	v_cvt_pk_bf16_f32 v146, v149, v150
	v_cvt_pk_bf16_f32 v147, v151, v136
	v_lshl_add_u64 v[136:137], s[10:11], 0, v[126:127]
	v_add_co_u32_e32 v136, vcc, s54, v136
	v_lshlrev_b32_e32 v143, 16, v118
	s_nop 0
	v_addc_co_u32_e32 v137, vcc, 0, v137, vcc
	s_waitcnt vmcnt(0)
; __device__ __forceinline__ unsigned pk2(float lo, float hi) { return pg8::cvt_pk_bf16(lo, hi); }
; __device__ __forceinline__ float bf_lo(unsigned w) { return __uint_as_float(w << 16); }
; __device__ __forceinline__ float bf_hi(unsigned w) { return __uint_as_float(w & 0xffff0000u); }
; __global__ void __launch_bounds__(512, 2) fwd_mega(Params P_by_kernarg) {
;     ...
;             for (int q = 0; q < 4; ++q) { const int rq = row + q * NGW; if (rq < MX) {
; #pragma unroll
;             for (int j = 0; j < 4; ++j) { const int col = (lane + 64 * j) * 8;
;                 const u32x4 a = av[q][j], bq = bv[q][j];
;                 float d[8]; d[0] = bf_lo(a.x) - lam * bf_lo(bq.x); d[1] = bf_hi(a.x) - lam * bf_hi(bq.x); d[2] = bf_lo(a.y) - lam * bf_lo(bq.y); d[3] = bf_hi(a.y) - lam * bf_hi(bq.y);
;                 d[4] = bf_lo(a.z) - lam * bf_lo(bq.z); d[5] = bf_hi(a.z) - lam * bf_hi(bq.z); d[6] = bf_lo(a.w) - lam * bf_lo(bq.w); d[7] = bf_hi(a.w) - lam * bf_hi(bq.w);
;                 float ss = 0.f;
; #pragma unroll
;                 for (int e = 0; e < 8; ++e) ss += d[e] * d[e];
;                 ss += __shfl_xor(ss, 1); ss += __shfl_xor(ss, 2); ss += __shfl_xor(ss, 4); ss += __shfl_xor(ss, 8); ss += __shfl_xor(ss, 16);
;                 const float rs = rsqrtf(ss * (1.f / 256.f) + EPS) * 0.8f;
;                 const f32x4 g0 = *(const f32x4*)(KA->in[8] + (col & 255)), g1 = *(const f32x4*)(KA->in[8] + (col & 255) + 4);
;                 u32x4 w; w.x = pk2(d[0] * rs * g0[0], d[1] * rs * g0[1]); w.y = pk2(d[2] * rs * g0[2], d[3] * rs * g0[3]); w.z = pk2(d[4] * rs * g1[0], d[5] * rs * g1[1]); w.w = pk2(d[6] * rs * g1[2], d[7] * rs * g1[3]);
;                 *(u32x4*)(Cat + (size_t)rq * DM + col) = w; } } }
	global_store_dwordx4 v[136:137], v[144:147], off
	s_nop 1
	s_nop 0
	v_lshlrev_b32_e32 v152, 16, v114
	v_and_b32_e32 v118, 0xffff0000, v118
	v_and_b32_e32 v114, 0xffff0000, v114
	v_fma_f32 v154, -v122, v114, v118
	v_lshlrev_b32_e32 v118, 16, v119
	v_and_b32_e32 v119, 0xffff0000, v119
	v_lshlrev_b32_e32 v114, 16, v115
	v_and_b32_e32 v115, 0xffff0000, v115
	v_fma_f32 v143, -v122, v152, v143
	v_mul_f32_e32 v152, v154, v154
	v_pk_fma_f32 v[114:115], v[122:123], v[114:115], v[118:119] neg_lo:[1,0,0] neg_hi:[1,0,0]
	v_fmac_f32_e32 v152, v143, v143
	v_pk_mul_f32 v[118:119], v[114:115], v[114:115]
	v_and_b32_e32 v153, 0xffff0000, v116
	v_add_f32_e32 v118, v152, v118
	v_add_f32_e32 v155, v118, v119
	v_lshlrev_b32_e32 v118, 16, v120
	v_and_b32_e32 v119, 0xffff0000, v120
	v_lshlrev_b32_e32 v152, 16, v116
	v_pk_fma_f32 v[118:119], v[122:123], v[152:153], v[118:119] neg_lo:[1,0,0] neg_hi:[1,0,0]
	v_lshlrev_b32_e32 v120, 16, v121
	v_pk_mul_f32 v[152:153], v[118:119], v[118:119]
	v_and_b32_e32 v121, 0xffff0000, v121
	v_add_f32_e32 v116, v155, v152
	v_add_f32_e32 v152, v116, v153
	v_lshlrev_b32_e32 v116, 16, v117
	v_and_b32_e32 v117, 0xffff0000, v117
	v_pk_fma_f32 v[116:117], v[122:123], v[116:117], v[120:121] neg_lo:[1,0,0] neg_hi:[1,0,0]
	v_lshlrev_b32_e32 v153, 16, v106
	v_pk_mul_f32 v[120:121], v[116:117], v[116:117]
	v_and_b32_e32 v106, 0xffff0000, v106
	v_add_f32_e32 v120, v152, v120
	v_add_f32_e32 v120, v120, v121
	ds_bpermute_b32 v121, v125, v120
	v_lshlrev_b32_e32 v152, 16, v110
	v_and_b32_e32 v110, 0xffff0000, v110
	s_waitcnt lgkmcnt(0)
	v_add_f32_e32 v120, v120, v121
	ds_bpermute_b32 v121, v138, v120
	s_waitcnt lgkmcnt(0)
	v_add_f32_e32 v120, v120, v121
	ds_bpermute_b32 v121, v139, v120
	s_waitcnt lgkmcnt(0)
	v_add_f32_e32 v120, v120, v121
	ds_bpermute_b32 v121, v140, v120
	s_waitcnt lgkmcnt(0)
	v_add_f32_e32 v120, v120, v121
	ds_bpermute_b32 v121, v141, v120
	s_waitcnt lgkmcnt(0)
	v_add_f32_e32 v120, v120, v121
	v_fmamk_f32 v120, v120, 0x3b800000, v142
	v_mul_f32_e32 v121, 0x4b800000, v120
	v_cmp_gt_f32_e32 vcc, s53, v120
	s_nop 1
	v_cndmask_b32_e32 v120, v120, v121, vcc
	v_rsq_f32_e32 v120, v120
	s_nop 0
	v_mul_f32_e32 v121, 0x45800000, v120
	v_cndmask_b32_e32 v120, v120, v121, vcc
	v_mul_f32_e32 v120, 0x3f4ccccd, v120
	v_mul_f32_e32 v115, v115, v120
	v_mul_f32_e32 v117, v117, v120
	v_mul_f32_e32 v121, v143, v120
	v_mul_f32_e32 v143, v154, v120
	v_mul_f32_e32 v114, v114, v120
	v_mul_f32_e32 v118, v118, v120
	v_mul_f32_e32 v119, v119, v120
	v_mul_f32_e32 v116, v116, v120
	v_mul_f32_e32 v115, v203, v115
	v_mul_f32_e32 v117, v207, v117
	v_mul_f32_e32 v120, v200, v121
	v_mul_f32_e32 v121, v201, v143
	v_mul_f32_e32 v143, v202, v114
	v_mul_f32_e32 v118, v204, v118
	v_mul_f32_e32 v119, v205, v119
	v_mul_f32_e32 v144, v206, v116
	v_cvt_pk_bf16_f32 v114, v120, v121
	v_cvt_pk_bf16_f32 v115, v143, v115
	v_cvt_pk_bf16_f32 v116, v118, v119
	v_cvt_pk_bf16_f32 v117, v144, v117
	global_store_dwordx4 v[136:137], v[114:117], off offset:1024
	s_nop 1
	s_nop 0
	v_fma_f32 v146, -v122, v106, v110
	v_lshlrev_b32_e32 v110, 16, v111
	v_and_b32_e32 v111, 0xffff0000, v111
	v_lshlrev_b32_e32 v106, 16, v107
	v_and_b32_e32 v107, 0xffff0000, v107
	v_fma_f32 v143, -v122, v153, v152
	v_mul_f32_e32 v144, v146, v146
	v_pk_fma_f32 v[106:107], v[122:123], v[106:107], v[110:111] neg_lo:[1,0,0] neg_hi:[1,0,0]
	v_fmac_f32_e32 v144, v143, v143
	v_pk_mul_f32 v[110:111], v[106:107], v[106:107]
	v_and_b32_e32 v145, 0xffff0000, v108
	v_add_f32_e32 v110, v144, v110
	v_add_f32_e32 v147, v110, v111
	v_lshlrev_b32_e32 v110, 16, v112
	v_and_b32_e32 v111, 0xffff0000, v112
	v_lshlrev_b32_e32 v144, 16, v108
	v_pk_fma_f32 v[110:111], v[122:123], v[144:145], v[110:111] neg_lo:[1,0,0] neg_hi:[1,0,0]
	v_lshlrev_b32_e32 v112, 16, v113
	v_pk_mul_f32 v[144:145], v[110:111], v[110:111]
	v_and_b32_e32 v113, 0xffff0000, v113
	v_add_f32_e32 v108, v147, v144
	v_add_f32_e32 v144, v108, v145
	v_lshlrev_b32_e32 v108, 16, v109
	v_and_b32_e32 v109, 0xffff0000, v109
	v_pk_fma_f32 v[108:109], v[122:123], v[108:109], v[112:113] neg_lo:[1,0,0] neg_hi:[1,0,0]
	v_lshlrev_b32_e32 v145, 16, v98
	v_pk_mul_f32 v[112:113], v[108:109], v[108:109]
	s_nop 0
	v_add_f32_e32 v112, v144, v112
	v_add_f32_e32 v112, v112, v113
	ds_bpermute_b32 v113, v125, v112
	v_lshlrev_b32_e32 v144, 16, v102
	s_waitcnt lgkmcnt(0)
; __device__ __forceinline__ unsigned pk2(float lo, float hi) { return pg8::cvt_pk_bf16(lo, hi); }
; __device__ __forceinline__ float bf_lo(unsigned w) { return __uint_as_float(w << 16); }
; __device__ __forceinline__ float bf_hi(unsigned w) { return __uint_as_float(w & 0xffff0000u); }
; __global__ void __launch_bounds__(512, 2) fwd_mega(Params P_by_kernarg) {
;     ...
;             for (int q = 0; q < 4; ++q) { const int rq = row + q * NGW; if (rq < MX) {
; #pragma unroll
;             for (int j = 0; j < 4; ++j) { const int col = (lane + 64 * j) * 8;
;                 const u32x4 a = av[q][j], bq = bv[q][j];
;                 float d[8]; d[0] = bf_lo(a.x) - lam * bf_lo(bq.x); d[1] = bf_hi(a.x) - lam * bf_hi(bq.x); d[2] = bf_lo(a.y) - lam * bf_lo(bq.y); d[3] = bf_hi(a.y) - lam * bf_hi(bq.y);
;                 d[4] = bf_lo(a.z) - lam * bf_lo(bq.z); d[5] = bf_hi(a.z) - lam * bf_hi(bq.z); d[6] = bf_lo(a.w) - lam * bf_lo(bq.w); d[7] = bf_hi(a.w) - lam * bf_hi(bq.w);
;                 float ss = 0.f;
; #pragma unroll
;                 for (int e = 0; e < 8; ++e) ss += d[e] * d[e];
;                 ss += __shfl_xor(ss, 1); ss += __shfl_xor(ss, 2); ss += __shfl_xor(ss, 4); ss += __shfl_xor(ss, 8); ss += __shfl_xor(ss, 16);
;                 const float rs = rsqrtf(ss * (1.f / 256.f) + EPS) * 0.8f;
;                 const f32x4 g0 = *(const f32x4*)(KA->in[8] + (col & 255)), g1 = *(const f32x4*)(KA->in[8] + (col & 255) + 4);
;                 u32x4 w; w.x = pk2(d[0] * rs * g0[0], d[1] * rs * g0[1]); w.y = pk2(d[2] * rs * g0[2], d[3] * rs * g0[3]); w.z = pk2(d[4] * rs * g1[0], d[5] * rs * g1[1]); w.w = pk2(d[6] * rs * g1[2], d[7] * rs * g1[3]);
;                 *(u32x4*)(Cat + (size_t)rq * DM + col) = w; } } }
	v_add_f32_e32 v112, v112, v113
	ds_bpermute_b32 v113, v138, v112
	s_waitcnt lgkmcnt(0)
	v_add_f32_e32 v112, v112, v113
	ds_bpermute_b32 v113, v139, v112
	s_waitcnt lgkmcnt(0)
	v_add_f32_e32 v112, v112, v113
	ds_bpermute_b32 v113, v140, v112
	s_waitcnt lgkmcnt(0)
	v_add_f32_e32 v112, v112, v113
	ds_bpermute_b32 v113, v141, v112
	s_waitcnt lgkmcnt(0)
	v_add_f32_e32 v112, v112, v113
	v_fmamk_f32 v112, v112, 0x3b800000, v142
	v_mul_f32_e32 v113, 0x4b800000, v112
	v_cmp_gt_f32_e32 vcc, s53, v112
	s_nop 1
	v_cndmask_b32_e32 v112, v112, v113, vcc
	v_rsq_f32_e32 v112, v112
	s_nop 0
	v_mul_f32_e32 v113, 0x45800000, v112
	v_cndmask_b32_e32 v112, v112, v113, vcc
	v_mul_f32_e32 v112, 0x3f4ccccd, v112
	v_mul_f32_e32 v107, v107, v112
	v_mul_f32_e32 v109, v109, v112
	v_mul_f32_e32 v113, v143, v112
	v_mul_f32_e32 v143, v146, v112
	v_mul_f32_e32 v106, v106, v112
	v_mul_f32_e32 v110, v110, v112
	v_mul_f32_e32 v111, v111, v112
	v_mul_f32_e32 v108, v108, v112
	v_mul_f32_e32 v107, v203, v107
	v_mul_f32_e32 v109, v207, v109
	v_mul_f32_e32 v112, v200, v113
	v_mul_f32_e32 v113, v201, v143
	v_mul_f32_e32 v118, v202, v106
	v_mul_f32_e32 v110, v204, v110
	v_mul_f32_e32 v111, v205, v111
	v_mul_f32_e32 v114, v206, v108
	v_cvt_pk_bf16_f32 v106, v112, v113
	v_cvt_pk_bf16_f32 v107, v118, v107
	v_cvt_pk_bf16_f32 v108, v110, v111
	v_cvt_pk_bf16_f32 v109, v114, v109
	global_store_dwordx4 v[136:137], v[106:109], off offset:2048
	s_nop 1
	s_nop 0
	v_and_b32_e32 v118, 0xffff0000, v102
	v_and_b32_e32 v119, 0xffff0000, v98
	v_lshlrev_b32_e32 v102, 16, v103
	v_and_b32_e32 v103, 0xffff0000, v103
	v_lshlrev_b32_e32 v98, 16, v99
	v_and_b32_e32 v99, 0xffff0000, v99
	v_fma_f32 v118, -v122, v119, v118
	v_lshlrev_b32_e32 v114, 16, v104
	v_and_b32_e32 v115, 0xffff0000, v104
	v_lshlrev_b32_e32 v116, 16, v100
	v_and_b32_e32 v117, 0xffff0000, v100
	v_lshlrev_b32_e32 v104, 16, v105
	v_and_b32_e32 v105, 0xffff0000, v105
	v_lshlrev_b32_e32 v100, 16, v101
	v_and_b32_e32 v101, 0xffff0000, v101
	v_fma_f32 v120, -v122, v145, v144
	v_pk_fma_f32 v[98:99], v[122:123], v[98:99], v[102:103] neg_lo:[1,0,0] neg_hi:[1,0,0]
	v_mul_f32_e32 v119, v118, v118
	v_pk_fma_f32 v[100:101], v[122:123], v[100:101], v[104:105] neg_lo:[1,0,0] neg_hi:[1,0,0]
	v_pk_mul_f32 v[104:105], v[98:99], v[98:99]
	v_fmac_f32_e32 v119, v120, v120
	v_pk_fma_f32 v[102:103], v[122:123], v[116:117], v[114:115] neg_lo:[1,0,0] neg_hi:[1,0,0]
	v_add_f32_e32 v104, v119, v104
	v_pk_mul_f32 v[114:115], v[102:103], v[102:103]
	v_add_f32_e32 v104, v104, v105
	v_add_f32_e32 v104, v104, v114
	v_pk_mul_f32 v[116:117], v[100:101], v[100:101]
	v_add_f32_e32 v104, v104, v115
	v_add_f32_e32 v104, v104, v116
	v_add_f32_e32 v104, v104, v117
	ds_bpermute_b32 v105, v125, v104
	s_waitcnt lgkmcnt(0)
	v_add_f32_e32 v104, v104, v105
	ds_bpermute_b32 v105, v138, v104
	s_waitcnt lgkmcnt(0)
	v_add_f32_e32 v104, v104, v105
	ds_bpermute_b32 v105, v139, v104
	s_waitcnt lgkmcnt(0)
	v_add_f32_e32 v104, v104, v105
	ds_bpermute_b32 v105, v140, v104
	s_waitcnt lgkmcnt(0)
	v_add_f32_e32 v104, v104, v105
	ds_bpermute_b32 v105, v141, v104
	s_waitcnt lgkmcnt(0)
	v_add_f32_e32 v104, v104, v105
	v_fmamk_f32 v104, v104, 0x3b800000, v142
	v_mul_f32_e32 v105, 0x4b800000, v104
	v_cmp_gt_f32_e32 vcc, s53, v104
	s_nop 1
	v_cndmask_b32_e32 v104, v104, v105, vcc
	v_rsq_f32_e32 v104, v104
	s_nop 0
	v_mul_f32_e32 v105, 0x45800000, v104
	v_cndmask_b32_e32 v104, v104, v105, vcc
	v_mul_f32_e32 v104, 0x3f4ccccd, v104
	v_mul_f32_e32 v105, v120, v104
	v_mul_f32_e32 v114, v118, v104
	v_mul_f32_e32 v98, v98, v104
	v_mul_f32_e32 v99, v99, v104
	v_mul_f32_e32 v101, v101, v104
	v_mul_f32_e32 v102, v102, v104
	v_mul_f32_e32 v103, v103, v104
	v_mul_f32_e32 v100, v100, v104
	v_mul_f32_e32 v104, v200, v105
	v_mul_f32_e32 v105, v201, v114
	v_mul_f32_e32 v110, v202, v98
	v_mul_f32_e32 v99, v203, v99
	v_mul_f32_e32 v101, v207, v101
	v_cvt_pk_bf16_f32 v98, v104, v105
	v_mul_f32_e32 v102, v204, v102
	v_mul_f32_e32 v103, v205, v103
	v_mul_f32_e32 v106, v206, v100
	v_cvt_pk_bf16_f32 v99, v110, v99
	v_cvt_pk_bf16_f32 v100, v102, v103
	v_cvt_pk_bf16_f32 v101, v106, v101
	global_store_dwordx4 v[136:137], v[98:101], off offset:3072
	s_nop 1
	v_lshlrev_b32_e32 v98, 2, v124
	s_cbranch_scc0 .LBB0_614
	s_andn2_b64 vcc, exec, s[48:49]
	s_cbranch_vccz .LBB0_615

; __device__ __forceinline__ unsigned pk2(float lo, float hi) { return pg8::cvt_pk_bf16(lo, hi); }
; __device__ __forceinline__ float bf_lo(unsigned w) { return __uint_as_float(w << 16); }
; __device__ __forceinline__ float bf_hi(unsigned w) { return __uint_as_float(w & 0xffff0000u); }
; __global__ void __launch_bounds__(512, 2) fwd_mega(Params P_by_kernarg) {
;     ...
;             for (int q = 0; q < 4; ++q) { const int rq = row + q * NGW; if (rq < MX) {
; #pragma unroll
;             for (int j = 0; j < 4; ++j) { const int col = (lane + 64 * j) * 8;
;                 const u32x4 a = av[q][j], bq = bv[q][j];
;                 float d[8]; d[0] = bf_lo(a.x) - lam * bf_lo(bq.x); d[1] = bf_hi(a.x) - lam * bf_hi(bq.x); d[2] = bf_lo(a.y) - lam * bf_lo(bq.y); d[3] = bf_hi(a.y) - lam * bf_hi(bq.y);
;                 d[4] = bf_lo(a.z) - lam * bf_lo(bq.z); d[5] = bf_hi(a.z) - lam * bf_hi(bq.z); d[6] = bf_lo(a.w) - lam * bf_lo(bq.w); d[7] = bf_hi(a.w) - lam * bf_hi(bq.w);
;                 float ss = 0.f;
; #pragma unroll
;                 for (int e = 0; e < 8; ++e) ss += d[e] * d[e];
;                 ss += __shfl_xor(ss, 1); ss += __shfl_xor(ss, 2); ss += __shfl_xor(ss, 4); ss += __shfl_xor(ss, 8); ss += __shfl_xor(ss, 16);
;                 const float rs = rsqrtf(ss * (1.f / 256.f) + EPS) * 0.8f;
;                 const f32x4 g0 = *(const f32x4*)(KA->in[8] + (col & 255)), g1 = *(const f32x4*)(KA->in[8] + (col & 255) + 4);
;                 u32x4 w; w.x = pk2(d[0] * rs * g0[0], d[1] * rs * g0[1]); w.y = pk2(d[2] * rs * g0[2], d[3] * rs * g0[3]); w.z = pk2(d[4] * rs * g1[0], d[5] * rs * g1[1]); w.w = pk2(d[6] * rs * g1[2], d[7] * rs * g1[3]);
;                 *(u32x4*)(Cat + (size_t)rq * DM + col) = w; } } }
.LBB0_614:
	s_load_dwordx2 s[50:51], s[4:5], 0x40
	v_lshlrev_b32_e32 v99, 16, v90
	v_lshlrev_b32_e32 v112, 16, v94
	v_and_b32_e32 v113, 0xffff0000, v90
	v_and_b32_e32 v114, 0xffff0000, v94
	s_waitcnt lgkmcnt(0)
	s_nop 1
	v_lshlrev_b32_e32 v90, 16, v91
	v_and_b32_e32 v91, 0xffff0000, v91
	v_lshlrev_b32_e32 v94, 16, v95
	v_and_b32_e32 v95, 0xffff0000, v95
	v_fma_f32 v99, -v122, v112, v99
	v_fma_f32 v112, -v122, v114, v113
	v_pk_fma_f32 v[94:95], v[122:123], v[94:95], v[90:91] neg_lo:[1,0,0] neg_hi:[1,0,0]
	v_mul_f32_e32 v113, v112, v112
	v_lshlrev_b32_e32 v108, 16, v92
	v_and_b32_e32 v109, 0xffff0000, v92
	v_lshlrev_b32_e32 v110, 16, v96
	v_and_b32_e32 v111, 0xffff0000, v96
	v_pk_mul_f32 v[90:91], v[94:95], v[94:95]
	v_fmac_f32_e32 v113, v99, v99
	v_lshlrev_b32_e32 v92, 16, v93
	v_and_b32_e32 v93, 0xffff0000, v93
	v_lshlrev_b32_e32 v96, 16, v97
	v_and_b32_e32 v97, 0xffff0000, v97
	v_pk_fma_f32 v[108:109], v[122:123], v[110:111], v[108:109] neg_lo:[1,0,0] neg_hi:[1,0,0]
	v_add_f32_e32 v90, v113, v90
	v_pk_fma_f32 v[92:93], v[122:123], v[96:97], v[92:93] neg_lo:[1,0,0] neg_hi:[1,0,0]
	v_pk_mul_f32 v[96:97], v[108:109], v[108:109]
	v_add_f32_e32 v90, v90, v91
	v_add_f32_e32 v90, v90, v96
	v_pk_mul_f32 v[110:111], v[92:93], v[92:93]
	v_add_f32_e32 v90, v90, v97
	v_add_f32_e32 v90, v90, v110
	v_add_f32_e32 v90, v90, v111
	ds_bpermute_b32 v91, v125, v90
	v_lshlrev_b32_e32 v110, 16, v82
	v_lshlrev_b32_e32 v111, 16, v86
	s_waitcnt lgkmcnt(0)
	v_add_f32_e32 v90, v90, v91
	ds_bpermute_b32 v91, v138, v90
	s_waitcnt lgkmcnt(0)
	v_add_f32_e32 v90, v90, v91
	ds_bpermute_b32 v91, v139, v90
	s_waitcnt lgkmcnt(0)
	v_add_f32_e32 v90, v90, v91
	ds_bpermute_b32 v91, v140, v90
	s_waitcnt lgkmcnt(0)
	v_add_f32_e32 v96, v90, v91
	ds_bpermute_b32 v97, v141, v96
	v_lshl_add_u64 v[90:91], s[40:41], 0, v[126:127]
	v_add_co_u32_e64 v90, s[2:3], s54, v90
	s_waitcnt lgkmcnt(0)
	v_add_f32_e32 v96, v96, v97
	v_fmamk_f32 v96, v96, 0x3b800000, v142
	v_mul_f32_e32 v97, 0x4b800000, v96
	v_cmp_gt_f32_e32 vcc, s53, v96
	v_addc_co_u32_e64 v91, s[2:3], 0, v91, s[2:3]
	s_nop 0
	v_cndmask_b32_e32 v96, v96, v97, vcc
	v_rsq_f32_e32 v96, v96
	s_nop 0
	v_mul_f32_e32 v97, 0x45800000, v96
	v_cndmask_b32_e32 v96, v96, v97, vcc
	v_mul_f32_e32 v96, 0x3f4ccccd, v96
	v_mul_f32_e32 v94, v94, v96
	v_mul_f32_e32 v95, v95, v96
	v_mul_f32_e32 v97, v99, v96
	v_mul_f32_e32 v99, v112, v96
	v_mul_f32_e32 v108, v108, v96
	v_mul_f32_e32 v109, v109, v96
	v_mul_f32_e32 v92, v92, v96
	v_mul_f32_e32 v93, v93, v96
	v_mul_f32_e32 v94, v202, v94
	v_mul_f32_e32 v95, v203, v95
	v_mul_f32_e32 v96, v200, v97
	v_mul_f32_e32 v97, v201, v99
	v_mul_f32_e32 v99, v204, v108
	v_mul_f32_e32 v100, v205, v109
	v_mul_f32_e32 v101, v206, v92
	v_mul_f32_e32 v102, v207, v93
	v_cvt_pk_bf16_f32 v92, v96, v97
	v_cvt_pk_bf16_f32 v93, v94, v95
	v_cvt_pk_bf16_f32 v94, v99, v100
	v_cvt_pk_bf16_f32 v95, v101, v102
	global_store_dwordx4 v[90:91], v[92:95], off
	s_nop 1
	s_nop 0
	v_and_b32_e32 v99, 0xffff0000, v82
	v_and_b32_e32 v106, 0xffff0000, v86
	v_lshlrev_b32_e32 v82, 16, v83
	v_and_b32_e32 v83, 0xffff0000, v83
	v_lshlrev_b32_e32 v86, 16, v87
	v_and_b32_e32 v87, 0xffff0000, v87
	v_fma_f32 v99, -v122, v106, v99
	v_lshlrev_b32_e32 v96, 16, v84
	v_and_b32_e32 v97, 0xffff0000, v84
	v_lshlrev_b32_e32 v104, 16, v88
	v_and_b32_e32 v105, 0xffff0000, v88
	v_lshlrev_b32_e32 v84, 16, v85
	v_and_b32_e32 v85, 0xffff0000, v85
	v_lshlrev_b32_e32 v88, 16, v89
	v_and_b32_e32 v89, 0xffff0000, v89
	v_fma_f32 v107, -v122, v111, v110
	v_pk_fma_f32 v[82:83], v[122:123], v[86:87], v[82:83] neg_lo:[1,0,0] neg_hi:[1,0,0]
	v_mul_f32_e32 v106, v99, v99
	v_pk_fma_f32 v[84:85], v[122:123], v[88:89], v[84:85] neg_lo:[1,0,0] neg_hi:[1,0,0]
	v_pk_mul_f32 v[88:89], v[82:83], v[82:83]
	v_fmac_f32_e32 v106, v107, v107
	v_pk_fma_f32 v[86:87], v[122:123], v[104:105], v[96:97] neg_lo:[1,0,0] neg_hi:[1,0,0]
	v_add_f32_e32 v88, v106, v88
	v_pk_mul_f32 v[96:97], v[86:87], v[86:87]
	v_add_f32_e32 v88, v88, v89
	v_add_f32_e32 v88, v88, v96
	v_pk_mul_f32 v[104:105], v[84:85], v[84:85]
	v_add_f32_e32 v88, v88, v97
	v_add_f32_e32 v88, v88, v104
	v_add_f32_e32 v88, v88, v105
	ds_bpermute_b32 v89, v125, v88
	v_lshlrev_b32_e32 v96, 16, v74
	v_lshlrev_b32_e32 v97, 16, v78
	v_fma_f32 v96, -v122, v97, v96
	s_waitcnt lgkmcnt(0)
	v_add_f32_e32 v88, v88, v89
	ds_bpermute_b32 v89, v138, v88
	s_waitcnt lgkmcnt(0)
	v_add_f32_e32 v88, v88, v89
	ds_bpermute_b32 v89, v139, v88
	s_waitcnt lgkmcnt(0)
	v_add_f32_e32 v88, v88, v89
	ds_bpermute_b32 v89, v140, v88
	s_waitcnt lgkmcnt(0)
	v_add_f32_e32 v88, v88, v89
	ds_bpermute_b32 v89, v141, v88
	s_waitcnt lgkmcnt(0)
; __device__ __forceinline__ unsigned pk2(float lo, float hi) { return pg8::cvt_pk_bf16(lo, hi); }
; __device__ __forceinline__ float bf_lo(unsigned w) { return __uint_as_float(w << 16); }
; __device__ __forceinline__ float bf_hi(unsigned w) { return __uint_as_float(w & 0xffff0000u); }
; __global__ void __launch_bounds__(512, 2) fwd_mega(Params P_by_kernarg) {
;     ...
;             for (int q = 0; q < 4; ++q) { const int rq = row + q * NGW; if (rq < MX) {
; #pragma unroll
;             for (int j = 0; j < 4; ++j) { const int col = (lane + 64 * j) * 8;
;                 const u32x4 a = av[q][j], bq = bv[q][j];
;                 float d[8]; d[0] = bf_lo(a.x) - lam * bf_lo(bq.x); d[1] = bf_hi(a.x) - lam * bf_hi(bq.x); d[2] = bf_lo(a.y) - lam * bf_lo(bq.y); d[3] = bf_hi(a.y) - lam * bf_hi(bq.y);
;                 d[4] = bf_lo(a.z) - lam * bf_lo(bq.z); d[5] = bf_hi(a.z) - lam * bf_hi(bq.z); d[6] = bf_lo(a.w) - lam * bf_lo(bq.w); d[7] = bf_hi(a.w) - lam * bf_hi(bq.w);
;                 float ss = 0.f;
; #pragma unroll
;                 for (int e = 0; e < 8; ++e) ss += d[e] * d[e];
;                 ss += __shfl_xor(ss, 1); ss += __shfl_xor(ss, 2); ss += __shfl_xor(ss, 4); ss += __shfl_xor(ss, 8); ss += __shfl_xor(ss, 16);
;                 const float rs = rsqrtf(ss * (1.f / 256.f) + EPS) * 0.8f;
;                 const f32x4 g0 = *(const f32x4*)(KA->in[8] + (col & 255)), g1 = *(const f32x4*)(KA->in[8] + (col & 255) + 4);
;                 u32x4 w; w.x = pk2(d[0] * rs * g0[0], d[1] * rs * g0[1]); w.y = pk2(d[2] * rs * g0[2], d[3] * rs * g0[3]); w.z = pk2(d[4] * rs * g1[0], d[5] * rs * g1[1]); w.w = pk2(d[6] * rs * g1[2], d[7] * rs * g1[3]);
;                 *(u32x4*)(Cat + (size_t)rq * DM + col) = w; } } }
	v_add_f32_e32 v88, v88, v89
	v_fmamk_f32 v88, v88, 0x3b800000, v142
	v_mul_f32_e32 v89, 0x4b800000, v88
	v_cmp_gt_f32_e32 vcc, s53, v88
	s_nop 1
	v_cndmask_b32_e32 v88, v88, v89, vcc
	v_rsq_f32_e32 v88, v88
	s_nop 0
	v_mul_f32_e32 v89, 0x45800000, v88
	v_cndmask_b32_e32 v88, v88, v89, vcc
	v_mul_f32_e32 v88, 0x3f4ccccd, v88
	v_mul_f32_e32 v83, v83, v88
	v_mul_f32_e32 v85, v85, v88
	v_mul_f32_e32 v89, v107, v88
	v_mul_f32_e32 v99, v99, v88
	v_mul_f32_e32 v82, v82, v88
	v_mul_f32_e32 v86, v86, v88
	v_mul_f32_e32 v87, v87, v88
	v_mul_f32_e32 v84, v84, v88
	v_mul_f32_e32 v83, v203, v83
	v_mul_f32_e32 v85, v207, v85
	v_mul_f32_e32 v88, v200, v89
	v_mul_f32_e32 v89, v201, v99
	v_mul_f32_e32 v99, v202, v82
	v_mul_f32_e32 v86, v204, v86
	v_mul_f32_e32 v87, v205, v87
	v_mul_f32_e32 v92, v206, v84
	v_cvt_pk_bf16_f32 v82, v88, v89
	v_cvt_pk_bf16_f32 v83, v99, v83
	v_cvt_pk_bf16_f32 v84, v86, v87
	v_cvt_pk_bf16_f32 v85, v92, v85
	global_store_dwordx4 v[90:91], v[82:85], off offset:1024
	s_nop 1
	s_nop 0
	v_and_b32_e32 v99, 0xffff0000, v74
	v_and_b32_e32 v100, 0xffff0000, v78
	v_lshlrev_b32_e32 v74, 16, v75
	v_and_b32_e32 v75, 0xffff0000, v75
	v_lshlrev_b32_e32 v78, 16, v79
	v_and_b32_e32 v79, 0xffff0000, v79
	v_fma_f32 v97, -v122, v100, v99
	v_lshlrev_b32_e32 v92, 16, v76
	v_and_b32_e32 v93, 0xffff0000, v76
	v_lshlrev_b32_e32 v94, 16, v80
	v_and_b32_e32 v95, 0xffff0000, v80
	v_lshlrev_b32_e32 v76, 16, v77
	v_and_b32_e32 v77, 0xffff0000, v77
	v_lshlrev_b32_e32 v80, 16, v81
	v_and_b32_e32 v81, 0xffff0000, v81
	v_pk_fma_f32 v[74:75], v[122:123], v[78:79], v[74:75] neg_lo:[1,0,0] neg_hi:[1,0,0]
	v_mul_f32_e32 v99, v97, v97
	v_pk_fma_f32 v[76:77], v[122:123], v[80:81], v[76:77] neg_lo:[1,0,0] neg_hi:[1,0,0]
	v_pk_mul_f32 v[80:81], v[74:75], v[74:75]
	v_fmac_f32_e32 v99, v96, v96
	v_pk_fma_f32 v[78:79], v[122:123], v[94:95], v[92:93] neg_lo:[1,0,0] neg_hi:[1,0,0]
	v_add_f32_e32 v80, v99, v80
	v_pk_mul_f32 v[92:93], v[78:79], v[78:79]
	v_add_f32_e32 v80, v80, v81
	v_add_f32_e32 v80, v80, v92
	v_pk_mul_f32 v[94:95], v[76:77], v[76:77]
	v_add_f32_e32 v80, v80, v93
	v_add_f32_e32 v80, v80, v94
	v_add_f32_e32 v80, v80, v95
	ds_bpermute_b32 v81, v125, v80
	v_lshlrev_b32_e32 v92, 16, v66
	v_lshlrev_b32_e32 v93, 16, v70
	s_waitcnt lgkmcnt(0)
	v_add_f32_e32 v80, v80, v81
	ds_bpermute_b32 v81, v138, v80
	s_waitcnt lgkmcnt(0)
	v_add_f32_e32 v80, v80, v81
	ds_bpermute_b32 v81, v139, v80
	s_waitcnt lgkmcnt(0)
	v_add_f32_e32 v80, v80, v81
	ds_bpermute_b32 v81, v140, v80
	s_waitcnt lgkmcnt(0)
	v_add_f32_e32 v80, v80, v81
	ds_bpermute_b32 v81, v141, v80
	s_waitcnt lgkmcnt(0)
	v_add_f32_e32 v80, v80, v81
	v_fmamk_f32 v80, v80, 0x3b800000, v142
	v_mul_f32_e32 v81, 0x4b800000, v80
	v_cmp_gt_f32_e32 vcc, s53, v80
	s_nop 1
	v_cndmask_b32_e32 v80, v80, v81, vcc
	v_rsq_f32_e32 v80, v80
	s_nop 0
	v_mul_f32_e32 v81, 0x45800000, v80
	v_cndmask_b32_e32 v80, v80, v81, vcc
	v_mul_f32_e32 v80, 0x3f4ccccd, v80
	v_mul_f32_e32 v75, v75, v80
	v_mul_f32_e32 v77, v77, v80
	v_mul_f32_e32 v81, v96, v80
	v_mul_f32_e32 v94, v97, v80
	v_mul_f32_e32 v74, v74, v80
	v_mul_f32_e32 v78, v78, v80
	v_mul_f32_e32 v79, v79, v80
	v_mul_f32_e32 v76, v76, v80
	v_mul_f32_e32 v75, v203, v75
	v_mul_f32_e32 v77, v207, v77
	v_mul_f32_e32 v80, v200, v81
	v_mul_f32_e32 v81, v201, v94
	v_mul_f32_e32 v86, v202, v74
	v_mul_f32_e32 v78, v204, v78
	v_mul_f32_e32 v79, v205, v79
	v_mul_f32_e32 v82, v206, v76
	v_cvt_pk_bf16_f32 v74, v80, v81
	v_cvt_pk_bf16_f32 v75, v86, v75
	v_cvt_pk_bf16_f32 v76, v78, v79
	v_cvt_pk_bf16_f32 v77, v82, v77
	global_store_dwordx4 v[90:91], v[74:77], off offset:2048
	s_nop 1
	s_nop 0
	v_and_b32_e32 v86, 0xffff0000, v66
	v_and_b32_e32 v87, 0xffff0000, v70
	v_lshlrev_b32_e32 v66, 16, v67
	v_and_b32_e32 v67, 0xffff0000, v67
	v_lshlrev_b32_e32 v70, 16, v71
	v_and_b32_e32 v71, 0xffff0000, v71
	v_fma_f32 v86, -v122, v87, v86
	v_lshlrev_b32_e32 v82, 16, v68
	v_and_b32_e32 v83, 0xffff0000, v68
	v_lshlrev_b32_e32 v84, 16, v72
	v_and_b32_e32 v85, 0xffff0000, v72
	v_lshlrev_b32_e32 v68, 16, v69
	v_and_b32_e32 v69, 0xffff0000, v69
	v_lshlrev_b32_e32 v72, 16, v73
	v_and_b32_e32 v73, 0xffff0000, v73
	v_fma_f32 v88, -v122, v93, v92
	v_pk_fma_f32 v[66:67], v[122:123], v[70:71], v[66:67] neg_lo:[1,0,0] neg_hi:[1,0,0]
	v_mul_f32_e32 v87, v86, v86
	v_pk_fma_f32 v[68:69], v[122:123], v[72:73], v[68:69] neg_lo:[1,0,0] neg_hi:[1,0,0]
	v_pk_mul_f32 v[72:73], v[66:67], v[66:67]
	v_fmac_f32_e32 v87, v88, v88
	v_pk_fma_f32 v[70:71], v[122:123], v[84:85], v[82:83] neg_lo:[1,0,0] neg_hi:[1,0,0]
	v_add_f32_e32 v72, v87, v72
	v_pk_mul_f32 v[82:83], v[70:71], v[70:71]
	v_add_f32_e32 v72, v72, v73
	v_add_f32_e32 v72, v72, v82
	v_pk_mul_f32 v[84:85], v[68:69], v[68:69]
	v_add_f32_e32 v72, v72, v83
	v_add_f32_e32 v72, v72, v84
	v_add_f32_e32 v72, v72, v85
	ds_bpermute_b32 v73, v125, v72
	s_waitcnt lgkmcnt(0)
	v_add_f32_e32 v72, v72, v73
	ds_bpermute_b32 v73, v138, v72
	s_waitcnt lgkmcnt(0)
	v_add_f32_e32 v72, v72, v73
	ds_bpermute_b32 v73, v139, v72
	s_waitcnt lgkmcnt(0)
	v_add_f32_e32 v72, v72, v73
	ds_bpermute_b32 v73, v140, v72
	s_waitcnt lgkmcnt(0)
	v_add_f32_e32 v72, v72, v73
	ds_bpermute_b32 v73, v141, v72
	s_waitcnt lgkmcnt(0)
	v_add_f32_e32 v72, v72, v73
	v_fmamk_f32 v72, v72, 0x3b800000, v142
	v_mul_f32_e32 v73, 0x4b800000, v72
	v_cmp_gt_f32_e32 vcc, s53, v72
	s_nop 1
	v_cndmask_b32_e32 v72, v72, v73, vcc
	v_rsq_f32_e32 v72, v72
	s_nop 0
	v_mul_f32_e32 v73, 0x45800000, v72
	v_cndmask_b32_e32 v72, v72, v73, vcc
	v_mul_f32_e32 v72, 0x3f4ccccd, v72
	v_mul_f32_e32 v67, v67, v72
	v_mul_f32_e32 v69, v69, v72
	v_mul_f32_e32 v73, v88, v72
	v_mul_f32_e32 v82, v86, v72
	v_mul_f32_e32 v66, v66, v72
	v_mul_f32_e32 v70, v70, v72
	v_mul_f32_e32 v71, v71, v72
	v_mul_f32_e32 v68, v68, v72
	v_mul_f32_e32 v67, v203, v67
	v_mul_f32_e32 v69, v207, v69
	v_mul_f32_e32 v72, v200, v73
	v_mul_f32_e32 v73, v201, v82
	v_mul_f32_e32 v78, v202, v66
	v_mul_f32_e32 v70, v204, v70
	v_mul_f32_e32 v71, v205, v71
	v_mul_f32_e32 v74, v206, v68
	v_cvt_pk_bf16_f32 v66, v72, v73
	v_cvt_pk_bf16_f32 v67, v78, v67
	v_cvt_pk_bf16_f32 v68, v70, v71
	v_cvt_pk_bf16_f32 v69, v74, v69
	global_store_dwordx4 v[90:91], v[66:69], off offset:3072
	s_andn2_b64 vcc, exec, s[48:49]
	s_cbranch_vccnz .LBB0_613
; __device__ __forceinline__ unsigned pk2(float lo, float hi) { return pg8::cvt_pk_bf16(lo, hi); }
; __device__ __forceinline__ float bf_lo(unsigned w) { return __uint_as_float(w << 16); }
; __device__ __forceinline__ float bf_hi(unsigned w) { return __uint_as_float(w & 0xffff0000u); }
; __global__ void __launch_bounds__(512, 2) fwd_mega(Params P_by_kernarg) {
;     ...
;             for (int q = 0; q < 4; ++q) { const int rq = row + q * NGW; if (rq < MX) {
; #pragma unroll
;             for (int j = 0; j < 4; ++j) { const int col = (lane + 64 * j) * 8;
;                 const u32x4 a = av[q][j], bq = bv[q][j];
;                 float d[8]; d[0] = bf_lo(a.x) - lam * bf_lo(bq.x); d[1] = bf_hi(a.x) - lam * bf_hi(bq.x); d[2] = bf_lo(a.y) - lam * bf_lo(bq.y); d[3] = bf_hi(a.y) - lam * bf_hi(bq.y);
;                 d[4] = bf_lo(a.z) - lam * bf_lo(bq.z); d[5] = bf_hi(a.z) - lam * bf_hi(bq.z); d[6] = bf_lo(a.w) - lam * bf_lo(bq.w); d[7] = bf_hi(a.w) - lam * bf_hi(bq.w);
;                 float ss = 0.f;
; #pragma unroll
;                 for (int e = 0; e < 8; ++e) ss += d[e] * d[e];
;                 ss += __shfl_xor(ss, 1); ss += __shfl_xor(ss, 2); ss += __shfl_xor(ss, 4); ss += __shfl_xor(ss, 8); ss += __shfl_xor(ss, 16);
;                 const float rs = rsqrtf(ss * (1.f / 256.f) + EPS) * 0.8f;
;                 const f32x4 g0 = *(const f32x4*)(KA->in[8] + (col & 255)), g1 = *(const f32x4*)(KA->in[8] + (col & 255) + 4);
;                 u32x4 w; w.x = pk2(d[0] * rs * g0[0], d[1] * rs * g0[1]); w.y = pk2(d[2] * rs * g0[2], d[3] * rs * g0[3]); w.z = pk2(d[4] * rs * g1[0], d[5] * rs * g1[1]); w.w = pk2(d[6] * rs * g1[2], d[7] * rs * g1[3]);
;                 *(u32x4*)(Cat + (size_t)rq * DM + col) = w; } } }
.LBB0_615:
	s_load_dwordx2 s[2:3], s[4:5], 0x40
	v_lshlrev_b32_e32 v78, 16, v58
	v_lshlrev_b32_e32 v79, 16, v62
	v_and_b32_e32 v80, 0xffff0000, v58
	v_and_b32_e32 v81, 0xffff0000, v62
	s_waitcnt lgkmcnt(0)
	s_nop 1
	v_lshlrev_b32_e32 v58, 16, v59
	v_and_b32_e32 v59, 0xffff0000, v59
	v_lshlrev_b32_e32 v62, 16, v63
	v_and_b32_e32 v63, 0xffff0000, v63
	v_fma_f32 v78, -v122, v79, v78
	v_fma_f32 v79, -v122, v81, v80
	v_pk_fma_f32 v[62:63], v[122:123], v[62:63], v[58:59] neg_lo:[1,0,0] neg_hi:[1,0,0]
	v_mul_f32_e32 v80, v79, v79
	v_lshlrev_b32_e32 v74, 16, v60
	v_and_b32_e32 v75, 0xffff0000, v60
	v_lshlrev_b32_e32 v76, 16, v64
	v_and_b32_e32 v77, 0xffff0000, v64
	v_pk_mul_f32 v[58:59], v[62:63], v[62:63]
	v_fmac_f32_e32 v80, v78, v78
	v_lshlrev_b32_e32 v60, 16, v61
	v_and_b32_e32 v61, 0xffff0000, v61
	v_lshlrev_b32_e32 v64, 16, v65
	v_and_b32_e32 v65, 0xffff0000, v65
	v_pk_fma_f32 v[74:75], v[122:123], v[76:77], v[74:75] neg_lo:[1,0,0] neg_hi:[1,0,0]
	v_add_f32_e32 v58, v80, v58
	v_pk_fma_f32 v[60:61], v[122:123], v[64:65], v[60:61] neg_lo:[1,0,0] neg_hi:[1,0,0]
	v_pk_mul_f32 v[64:65], v[74:75], v[74:75]
	v_add_f32_e32 v58, v58, v59
	v_add_f32_e32 v58, v58, v64
	v_pk_mul_f32 v[76:77], v[60:61], v[60:61]
	v_add_f32_e32 v58, v58, v65
	v_add_f32_e32 v58, v58, v76
	v_add_f32_e32 v58, v58, v77
	ds_bpermute_b32 v59, v125, v58
	s_ashr_i32 s47, s46, 31
	s_lshl_b64 s[46:47], s[46:47], 13
	v_lshlrev_b32_e32 v76, 16, v50
	v_lshlrev_b32_e32 v77, 16, v54
	s_waitcnt lgkmcnt(0)
	v_add_f32_e32 v58, v58, v59
	ds_bpermute_b32 v59, v138, v58
	s_waitcnt lgkmcnt(0)
	v_add_f32_e32 v58, v58, v59
	ds_bpermute_b32 v59, v139, v58
	s_waitcnt lgkmcnt(0)
	v_add_f32_e32 v58, v58, v59
	ds_bpermute_b32 v59, v140, v58
	s_waitcnt lgkmcnt(0)
	v_add_f32_e32 v58, v58, v59
	ds_bpermute_b32 v59, v141, v58
	s_waitcnt lgkmcnt(0)
	v_add_f32_e32 v58, v58, v59
	v_fmamk_f32 v58, v58, 0x3b800000, v142
	v_mul_f32_e32 v59, 0x4b800000, v58
	v_cmp_gt_f32_e32 vcc, s53, v58
	s_nop 1
	v_cndmask_b32_e32 v58, v58, v59, vcc
	v_rsq_f32_e32 v64, v58
	v_lshl_add_u64 v[58:59], v[134:135], 0, s[46:47]
	v_mul_f32_e32 v65, 0x45800000, v64
	v_cndmask_b32_e32 v64, v64, v65, vcc
	v_mul_f32_e32 v64, 0x3f4ccccd, v64
	v_mul_f32_e32 v62, v62, v64
	v_mul_f32_e32 v63, v63, v64
	v_mul_f32_e32 v65, v78, v64
	v_mul_f32_e32 v78, v79, v64
	v_mul_f32_e32 v74, v74, v64
	v_mul_f32_e32 v75, v75, v64
	v_mul_f32_e32 v60, v60, v64
	v_mul_f32_e32 v61, v61, v64
	v_mul_f32_e32 v62, v202, v62
	v_mul_f32_e32 v63, v203, v63
	v_mul_f32_e32 v64, v200, v65
	v_mul_f32_e32 v65, v201, v78
	v_mul_f32_e32 v66, v204, v74
	v_mul_f32_e32 v67, v205, v75
	v_mul_f32_e32 v68, v206, v60
	v_mul_f32_e32 v69, v207, v61
	v_cvt_pk_bf16_f32 v60, v64, v65
	v_cvt_pk_bf16_f32 v61, v62, v63
	v_cvt_pk_bf16_f32 v62, v66, v67
	v_cvt_pk_bf16_f32 v63, v68, v69
	global_store_dwordx4 v[58:59], v[60:63], off
	s_nop 1
	s_nop 0
	v_and_b32_e32 v72, 0xffff0000, v50
	v_and_b32_e32 v73, 0xffff0000, v54
	v_lshlrev_b32_e32 v50, 16, v51
	v_and_b32_e32 v51, 0xffff0000, v51
	v_lshlrev_b32_e32 v54, 16, v55
	v_and_b32_e32 v55, 0xffff0000, v55
	v_fma_f32 v72, -v122, v73, v72
	v_lshlrev_b32_e32 v68, 16, v52
	v_and_b32_e32 v69, 0xffff0000, v52
	v_lshlrev_b32_e32 v70, 16, v56
	v_and_b32_e32 v71, 0xffff0000, v56
	v_lshlrev_b32_e32 v52, 16, v53
	v_and_b32_e32 v53, 0xffff0000, v53
	v_lshlrev_b32_e32 v56, 16, v57
	v_and_b32_e32 v57, 0xffff0000, v57
	v_fma_f32 v74, -v122, v77, v76
	v_pk_fma_f32 v[50:51], v[122:123], v[54:55], v[50:51] neg_lo:[1,0,0] neg_hi:[1,0,0]
	v_mul_f32_e32 v73, v72, v72
	v_pk_fma_f32 v[52:53], v[122:123], v[56:57], v[52:53] neg_lo:[1,0,0] neg_hi:[1,0,0]
	v_pk_mul_f32 v[56:57], v[50:51], v[50:51]
	v_fmac_f32_e32 v73, v74, v74
	v_pk_fma_f32 v[54:55], v[122:123], v[70:71], v[68:69] neg_lo:[1,0,0] neg_hi:[1,0,0]
	v_add_f32_e32 v56, v73, v56
	v_pk_mul_f32 v[68:69], v[54:55], v[54:55]
	v_add_f32_e32 v56, v56, v57
	v_add_f32_e32 v56, v56, v68
	v_pk_mul_f32 v[70:71], v[52:53], v[52:53]
	v_add_f32_e32 v56, v56, v69
	v_add_f32_e32 v56, v56, v70
	v_add_f32_e32 v56, v56, v71
	ds_bpermute_b32 v57, v125, v56
	v_lshlrev_b32_e32 v68, 16, v42
	v_lshlrev_b32_e32 v69, 16, v46
	s_waitcnt lgkmcnt(0)
	v_add_f32_e32 v56, v56, v57
	ds_bpermute_b32 v57, v138, v56
	s_waitcnt lgkmcnt(0)
	v_add_f32_e32 v56, v56, v57
	ds_bpermute_b32 v57, v139, v56
	s_waitcnt lgkmcnt(0)
	v_add_f32_e32 v56, v56, v57
	ds_bpermute_b32 v57, v140, v56
	s_waitcnt lgkmcnt(0)
	v_add_f32_e32 v56, v56, v57
	ds_bpermute_b32 v57, v141, v56
	s_waitcnt lgkmcnt(0)
	v_add_f32_e32 v56, v56, v57
	v_fmamk_f32 v56, v56, 0x3b800000, v142
	v_mul_f32_e32 v57, 0x4b800000, v56
	v_cmp_gt_f32_e32 vcc, s53, v56
	s_nop 1
	v_cndmask_b32_e32 v56, v56, v57, vcc
	v_rsq_f32_e32 v56, v56
	s_nop 0
	v_mul_f32_e32 v57, 0x45800000, v56
	v_cndmask_b32_e32 v56, v56, v57, vcc
	v_mul_f32_e32 v56, 0x3f4ccccd, v56
	v_mul_f32_e32 v51, v51, v56
	v_mul_f32_e32 v53, v53, v56
	v_mul_f32_e32 v57, v74, v56
	v_mul_f32_e32 v70, v72, v56
	v_mul_f32_e32 v50, v50, v56
	v_mul_f32_e32 v54, v54, v56
	v_mul_f32_e32 v55, v55, v56
	v_mul_f32_e32 v52, v52, v56
	v_mul_f32_e32 v51, v203, v51
	v_mul_f32_e32 v53, v207, v53
	v_mul_f32_e32 v56, v200, v57
	v_mul_f32_e32 v57, v201, v70
	v_mul_f32_e32 v64, v202, v50
	v_mul_f32_e32 v54, v204, v54
	v_mul_f32_e32 v55, v205, v55
	v_mul_f32_e32 v60, v206, v52
	v_cvt_pk_bf16_f32 v50, v56, v57
	v_cvt_pk_bf16_f32 v51, v64, v51
	v_cvt_pk_bf16_f32 v52, v54, v55
	v_cvt_pk_bf16_f32 v53, v60, v53
	global_store_dwordx4 v[58:59], v[50:53], off offset:1024
	s_nop 1
	s_nop 0
	v_and_b32_e32 v64, 0xffff0000, v42
	v_and_b32_e32 v65, 0xffff0000, v46
	v_lshlrev_b32_e32 v42, 16, v43
	v_and_b32_e32 v43, 0xffff0000, v43
	v_lshlrev_b32_e32 v46, 16, v47
	v_and_b32_e32 v47, 0xffff0000, v47
	v_fma_f32 v64, -v122, v65, v64
	v_lshlrev_b32_e32 v60, 16, v44
	v_and_b32_e32 v61, 0xffff0000, v44
	v_lshlrev_b32_e32 v62, 16, v48
	v_and_b32_e32 v63, 0xffff0000, v48
	v_lshlrev_b32_e32 v44, 16, v45
	v_and_b32_e32 v45, 0xffff0000, v45
	v_lshlrev_b32_e32 v48, 16, v49
	v_and_b32_e32 v49, 0xffff0000, v49
	v_fma_f32 v66, -v122, v69, v68
	v_pk_fma_f32 v[42:43], v[122:123], v[46:47], v[42:43] neg_lo:[1,0,0] neg_hi:[1,0,0]
	v_mul_f32_e32 v65, v64, v64
	v_pk_fma_f32 v[44:45], v[122:123], v[48:49], v[44:45] neg_lo:[1,0,0] neg_hi:[1,0,0]
	v_pk_mul_f32 v[48:49], v[42:43], v[42:43]
	v_fmac_f32_e32 v65, v66, v66
	v_pk_fma_f32 v[46:47], v[122:123], v[62:63], v[60:61] neg_lo:[1,0,0] neg_hi:[1,0,0]
	v_add_f32_e32 v48, v65, v48
	v_pk_mul_f32 v[60:61], v[46:47], v[46:47]
	v_add_f32_e32 v48, v48, v49
	v_add_f32_e32 v48, v48, v60
	v_pk_mul_f32 v[62:63], v[44:45], v[44:45]
	v_add_f32_e32 v48, v48, v61
	v_add_f32_e32 v48, v48, v62
	v_add_f32_e32 v48, v48, v63
	ds_bpermute_b32 v49, v125, v48
	v_lshlrev_b32_e32 v60, 16, v34
	v_lshlrev_b32_e32 v61, 16, v38
	s_waitcnt lgkmcnt(0)
; __device__ __forceinline__ unsigned pk2(float lo, float hi) { return pg8::cvt_pk_bf16(lo, hi); }
; __device__ __forceinline__ float bf_lo(unsigned w) { return __uint_as_float(w << 16); }
; __device__ __forceinline__ float bf_hi(unsigned w) { return __uint_as_float(w & 0xffff0000u); }
; __global__ void __launch_bounds__(512, 2) fwd_mega(Params P_by_kernarg) {
;     ...
;             for (int q = 0; q < 4; ++q) { const int rq = row + q * NGW; if (rq < MX) {
; #pragma unroll
;             for (int j = 0; j < 4; ++j) { const int col = (lane + 64 * j) * 8;
;                 const u32x4 a = av[q][j], bq = bv[q][j];
;                 float d[8]; d[0] = bf_lo(a.x) - lam * bf_lo(bq.x); d[1] = bf_hi(a.x) - lam * bf_hi(bq.x); d[2] = bf_lo(a.y) - lam * bf_lo(bq.y); d[3] = bf_hi(a.y) - lam * bf_hi(bq.y);
;                 d[4] = bf_lo(a.z) - lam * bf_lo(bq.z); d[5] = bf_hi(a.z) - lam * bf_hi(bq.z); d[6] = bf_lo(a.w) - lam * bf_lo(bq.w); d[7] = bf_hi(a.w) - lam * bf_hi(bq.w);
;                 float ss = 0.f;
; #pragma unroll
;                 for (int e = 0; e < 8; ++e) ss += d[e] * d[e];
;                 ss += __shfl_xor(ss, 1); ss += __shfl_xor(ss, 2); ss += __shfl_xor(ss, 4); ss += __shfl_xor(ss, 8); ss += __shfl_xor(ss, 16);
;                 const float rs = rsqrtf(ss * (1.f / 256.f) + EPS) * 0.8f;
;                 const f32x4 g0 = *(const f32x4*)(KA->in[8] + (col & 255)), g1 = *(const f32x4*)(KA->in[8] + (col & 255) + 4);
;                 u32x4 w; w.x = pk2(d[0] * rs * g0[0], d[1] * rs * g0[1]); w.y = pk2(d[2] * rs * g0[2], d[3] * rs * g0[3]); w.z = pk2(d[4] * rs * g1[0], d[5] * rs * g1[1]); w.w = pk2(d[6] * rs * g1[2], d[7] * rs * g1[3]);
;                 *(u32x4*)(Cat + (size_t)rq * DM + col) = w; } } }
	v_add_f32_e32 v48, v48, v49
	ds_bpermute_b32 v49, v138, v48
	s_waitcnt lgkmcnt(0)
	v_add_f32_e32 v48, v48, v49
	ds_bpermute_b32 v49, v139, v48
	s_waitcnt lgkmcnt(0)
	v_add_f32_e32 v48, v48, v49
	ds_bpermute_b32 v49, v140, v48
	s_waitcnt lgkmcnt(0)
	v_add_f32_e32 v48, v48, v49
	ds_bpermute_b32 v49, v141, v48
	s_waitcnt lgkmcnt(0)
	v_add_f32_e32 v48, v48, v49
	v_fmamk_f32 v48, v48, 0x3b800000, v142
	v_mul_f32_e32 v49, 0x4b800000, v48
	v_cmp_gt_f32_e32 vcc, s53, v48
	s_nop 1
	v_cndmask_b32_e32 v48, v48, v49, vcc
	v_rsq_f32_e32 v48, v48
	s_nop 0
	v_mul_f32_e32 v49, 0x45800000, v48
	v_cndmask_b32_e32 v48, v48, v49, vcc
	v_mul_f32_e32 v48, 0x3f4ccccd, v48
	v_mul_f32_e32 v43, v43, v48
	v_mul_f32_e32 v45, v45, v48
	v_mul_f32_e32 v49, v66, v48
	v_mul_f32_e32 v62, v64, v48
	v_mul_f32_e32 v42, v42, v48
	v_mul_f32_e32 v46, v46, v48
	v_mul_f32_e32 v47, v47, v48
	v_mul_f32_e32 v44, v44, v48
	v_mul_f32_e32 v43, v203, v43
	v_mul_f32_e32 v45, v207, v45
	v_mul_f32_e32 v48, v200, v49
	v_mul_f32_e32 v49, v201, v62
	v_mul_f32_e32 v54, v202, v42
	v_mul_f32_e32 v46, v204, v46
	v_mul_f32_e32 v47, v205, v47
	v_mul_f32_e32 v50, v206, v44
	v_cvt_pk_bf16_f32 v42, v48, v49
	v_cvt_pk_bf16_f32 v43, v54, v43
	v_cvt_pk_bf16_f32 v44, v46, v47
	v_cvt_pk_bf16_f32 v45, v50, v45
	global_store_dwordx4 v[58:59], v[42:45], off offset:2048
	s_nop 1
	s_nop 0
	v_and_b32_e32 v54, 0xffff0000, v34
	v_and_b32_e32 v55, 0xffff0000, v38
	v_lshlrev_b32_e32 v34, 16, v35
	v_and_b32_e32 v35, 0xffff0000, v35
	v_lshlrev_b32_e32 v38, 16, v39
	v_and_b32_e32 v39, 0xffff0000, v39
	v_fma_f32 v54, -v122, v55, v54
	v_lshlrev_b32_e32 v50, 16, v36
	v_and_b32_e32 v51, 0xffff0000, v36
	v_lshlrev_b32_e32 v52, 16, v40
	v_and_b32_e32 v53, 0xffff0000, v40
	v_lshlrev_b32_e32 v36, 16, v37
	v_and_b32_e32 v37, 0xffff0000, v37
	v_lshlrev_b32_e32 v40, 16, v41
	v_and_b32_e32 v41, 0xffff0000, v41
	v_fma_f32 v56, -v122, v61, v60
	v_pk_fma_f32 v[34:35], v[122:123], v[38:39], v[34:35] neg_lo:[1,0,0] neg_hi:[1,0,0]
	v_mul_f32_e32 v55, v54, v54
	v_pk_fma_f32 v[36:37], v[122:123], v[40:41], v[36:37] neg_lo:[1,0,0] neg_hi:[1,0,0]
	v_pk_mul_f32 v[40:41], v[34:35], v[34:35]
	v_fmac_f32_e32 v55, v56, v56
	v_pk_fma_f32 v[38:39], v[122:123], v[52:53], v[50:51] neg_lo:[1,0,0] neg_hi:[1,0,0]
	v_add_f32_e32 v40, v55, v40
	v_pk_mul_f32 v[50:51], v[38:39], v[38:39]
	v_add_f32_e32 v40, v40, v41
	v_add_f32_e32 v40, v40, v50
	v_pk_mul_f32 v[52:53], v[36:37], v[36:37]
	v_add_f32_e32 v40, v40, v51
	v_add_f32_e32 v40, v40, v52
	v_add_f32_e32 v40, v40, v53
	ds_bpermute_b32 v41, v125, v40
	s_waitcnt lgkmcnt(0)
	v_add_f32_e32 v40, v40, v41
	ds_bpermute_b32 v41, v138, v40
	s_waitcnt lgkmcnt(0)
	v_add_f32_e32 v40, v40, v41
	ds_bpermute_b32 v41, v139, v40
	s_waitcnt lgkmcnt(0)
	v_add_f32_e32 v40, v40, v41
	ds_bpermute_b32 v41, v140, v40
	s_waitcnt lgkmcnt(0)
	v_add_f32_e32 v40, v40, v41
	ds_bpermute_b32 v41, v141, v40
	s_waitcnt lgkmcnt(0)
	v_add_f32_e32 v40, v40, v41
	v_fmamk_f32 v40, v40, 0x3b800000, v142
	v_mul_f32_e32 v41, 0x4b800000, v40
	v_cmp_gt_f32_e32 vcc, s53, v40
	s_nop 1
	v_cndmask_b32_e32 v40, v40, v41, vcc
	v_rsq_f32_e32 v40, v40
	s_nop 0
	v_mul_f32_e32 v41, 0x45800000, v40
	v_cndmask_b32_e32 v40, v40, v41, vcc
	v_mul_f32_e32 v40, 0x3f4ccccd, v40
	v_mul_f32_e32 v35, v35, v40
	v_mul_f32_e32 v37, v37, v40
	v_mul_f32_e32 v41, v56, v40
	v_mul_f32_e32 v50, v54, v40
	v_mul_f32_e32 v34, v34, v40
	v_mul_f32_e32 v38, v38, v40
	v_mul_f32_e32 v39, v39, v40
	v_mul_f32_e32 v36, v36, v40
	v_mul_f32_e32 v35, v203, v35
	v_mul_f32_e32 v37, v207, v37
	v_mul_f32_e32 v40, v200, v41
	v_mul_f32_e32 v41, v201, v50
	v_mul_f32_e32 v46, v202, v34
	v_mul_f32_e32 v38, v204, v38
	v_mul_f32_e32 v39, v205, v39
	v_mul_f32_e32 v42, v206, v36
	v_cvt_pk_bf16_f32 v34, v40, v41
	v_cvt_pk_bf16_f32 v35, v46, v35
	v_cvt_pk_bf16_f32 v36, v38, v39
	v_cvt_pk_bf16_f32 v37, v42, v37
	global_store_dwordx4 v[58:59], v[34:37], off offset:3072
	s_andn2_b64 vcc, exec, s[44:45]
	s_cbranch_vccnz .LBB0_610
.LBB0_616:
	s_load_dwordx2 s[2:3], s[4:5], 0x40
	v_lshlrev_b32_e32 v46, 16, v26
	v_lshlrev_b32_e32 v47, 16, v30
	v_and_b32_e32 v48, 0xffff0000, v26
	v_and_b32_e32 v49, 0xffff0000, v30
	s_waitcnt lgkmcnt(0)
	s_nop 1
	v_lshlrev_b32_e32 v26, 16, v27
	v_and_b32_e32 v27, 0xffff0000, v27
	v_lshlrev_b32_e32 v30, 16, v31
	v_and_b32_e32 v31, 0xffff0000, v31
	v_fma_f32 v46, -v122, v47, v46
	v_fma_f32 v47, -v122, v49, v48
	v_pk_fma_f32 v[30:31], v[122:123], v[30:31], v[26:27] neg_lo:[1,0,0] neg_hi:[1,0,0]
	v_mul_f32_e32 v48, v47, v47
	v_lshlrev_b32_e32 v42, 16, v28
	v_and_b32_e32 v43, 0xffff0000, v28
	v_lshlrev_b32_e32 v44, 16, v32
	v_and_b32_e32 v45, 0xffff0000, v32
	v_pk_mul_f32 v[26:27], v[30:31], v[30:31]
	v_fmac_f32_e32 v48, v46, v46
	v_lshlrev_b32_e32 v28, 16, v29
	v_and_b32_e32 v29, 0xffff0000, v29
	v_lshlrev_b32_e32 v32, 16, v33
	v_and_b32_e32 v33, 0xffff0000, v33
	v_pk_fma_f32 v[42:43], v[122:123], v[44:45], v[42:43] neg_lo:[1,0,0] neg_hi:[1,0,0]
	v_add_f32_e32 v26, v48, v26
	v_pk_fma_f32 v[28:29], v[122:123], v[32:33], v[28:29] neg_lo:[1,0,0] neg_hi:[1,0,0]
	v_pk_mul_f32 v[32:33], v[42:43], v[42:43]
	v_add_f32_e32 v26, v26, v27
	v_add_f32_e32 v26, v26, v32
	v_pk_mul_f32 v[44:45], v[28:29], v[28:29]
	v_add_f32_e32 v26, v26, v33
	v_add_f32_e32 v26, v26, v44
	v_add_f32_e32 v26, v26, v45
	ds_bpermute_b32 v27, v125, v26
	s_ashr_i32 s43, s42, 31
	s_lshl_b64 s[42:43], s[42:43], 13
	v_lshlrev_b32_e32 v44, 16, v18
	v_lshlrev_b32_e32 v45, 16, v22
	s_waitcnt lgkmcnt(0)
	v_add_f32_e32 v26, v26, v27
	ds_bpermute_b32 v27, v138, v26
	s_waitcnt lgkmcnt(0)
	v_add_f32_e32 v26, v26, v27
	ds_bpermute_b32 v27, v139, v26
	s_waitcnt lgkmcnt(0)
	v_add_f32_e32 v26, v26, v27
	ds_bpermute_b32 v27, v140, v26
	s_waitcnt lgkmcnt(0)
; __device__ __forceinline__ unsigned pk2(float lo, float hi) { return pg8::cvt_pk_bf16(lo, hi); }
; __device__ __forceinline__ float bf_lo(unsigned w) { return __uint_as_float(w << 16); }
; __device__ __forceinline__ float bf_hi(unsigned w) { return __uint_as_float(w & 0xffff0000u); }
; __global__ void __launch_bounds__(512, 2) fwd_mega(Params P_by_kernarg) {
;     ...
;             for (int q = 0; q < 4; ++q) { const int rq = row + q * NGW; if (rq < MX) {
; #pragma unroll
;             for (int j = 0; j < 4; ++j) { const int col = (lane + 64 * j) * 8;
;                 const u32x4 a = av[q][j], bq = bv[q][j];
;                 float d[8]; d[0] = bf_lo(a.x) - lam * bf_lo(bq.x); d[1] = bf_hi(a.x) - lam * bf_hi(bq.x); d[2] = bf_lo(a.y) - lam * bf_lo(bq.y); d[3] = bf_hi(a.y) - lam * bf_hi(bq.y);
;                 d[4] = bf_lo(a.z) - lam * bf_lo(bq.z); d[5] = bf_hi(a.z) - lam * bf_hi(bq.z); d[6] = bf_lo(a.w) - lam * bf_lo(bq.w); d[7] = bf_hi(a.w) - lam * bf_hi(bq.w);
;                 float ss = 0.f;
; #pragma unroll
;                 for (int e = 0; e < 8; ++e) ss += d[e] * d[e];
;                 ss += __shfl_xor(ss, 1); ss += __shfl_xor(ss, 2); ss += __shfl_xor(ss, 4); ss += __shfl_xor(ss, 8); ss += __shfl_xor(ss, 16);
;                 const float rs = rsqrtf(ss * (1.f / 256.f) + EPS) * 0.8f;
;                 const f32x4 g0 = *(const f32x4*)(KA->in[8] + (col & 255)), g1 = *(const f32x4*)(KA->in[8] + (col & 255) + 4);
;                 u32x4 w; w.x = pk2(d[0] * rs * g0[0], d[1] * rs * g0[1]); w.y = pk2(d[2] * rs * g0[2], d[3] * rs * g0[3]); w.z = pk2(d[4] * rs * g1[0], d[5] * rs * g1[1]); w.w = pk2(d[6] * rs * g1[2], d[7] * rs * g1[3]);
;                 *(u32x4*)(Cat + (size_t)rq * DM + col) = w; } } }
	v_add_f32_e32 v26, v26, v27
	ds_bpermute_b32 v27, v141, v26
	s_waitcnt lgkmcnt(0)
	v_add_f32_e32 v26, v26, v27
	v_fmamk_f32 v26, v26, 0x3b800000, v142
	v_mul_f32_e32 v27, 0x4b800000, v26
	v_cmp_gt_f32_e32 vcc, s53, v26
	s_nop 1
	v_cndmask_b32_e32 v26, v26, v27, vcc
	v_rsq_f32_e32 v32, v26
	v_lshl_add_u64 v[26:27], v[134:135], 0, s[42:43]
	v_mul_f32_e32 v33, 0x45800000, v32
	v_cndmask_b32_e32 v32, v32, v33, vcc
	v_mul_f32_e32 v32, 0x3f4ccccd, v32
	v_mul_f32_e32 v30, v30, v32
	v_mul_f32_e32 v31, v31, v32
	v_mul_f32_e32 v33, v46, v32
	v_mul_f32_e32 v46, v47, v32
	v_mul_f32_e32 v42, v42, v32
	v_mul_f32_e32 v43, v43, v32
	v_mul_f32_e32 v28, v28, v32
	v_mul_f32_e32 v29, v29, v32
	v_mul_f32_e32 v30, v202, v30
	v_mul_f32_e32 v31, v203, v31
	v_mul_f32_e32 v32, v200, v33
	v_mul_f32_e32 v33, v201, v46
	v_mul_f32_e32 v34, v204, v42
	v_mul_f32_e32 v35, v205, v43
	v_mul_f32_e32 v36, v206, v28
	v_mul_f32_e32 v37, v207, v29
	v_cvt_pk_bf16_f32 v28, v32, v33
	v_cvt_pk_bf16_f32 v29, v30, v31
	v_cvt_pk_bf16_f32 v30, v34, v35
	v_cvt_pk_bf16_f32 v31, v36, v37
	global_store_dwordx4 v[26:27], v[28:31], off
	s_nop 1
	s_nop 0
	v_and_b32_e32 v40, 0xffff0000, v18
	v_and_b32_e32 v41, 0xffff0000, v22
	v_lshlrev_b32_e32 v18, 16, v19
	v_and_b32_e32 v19, 0xffff0000, v19
	v_lshlrev_b32_e32 v22, 16, v23
	v_and_b32_e32 v23, 0xffff0000, v23
	v_fma_f32 v40, -v122, v41, v40
	v_lshlrev_b32_e32 v36, 16, v20
	v_and_b32_e32 v37, 0xffff0000, v20
	v_lshlrev_b32_e32 v38, 16, v24
	v_and_b32_e32 v39, 0xffff0000, v24
	v_lshlrev_b32_e32 v20, 16, v21
	v_and_b32_e32 v21, 0xffff0000, v21
	v_lshlrev_b32_e32 v24, 16, v25
	v_and_b32_e32 v25, 0xffff0000, v25
	v_fma_f32 v42, -v122, v45, v44
	v_pk_fma_f32 v[18:19], v[122:123], v[22:23], v[18:19] neg_lo:[1,0,0] neg_hi:[1,0,0]
	v_mul_f32_e32 v41, v40, v40
	v_pk_fma_f32 v[20:21], v[122:123], v[24:25], v[20:21] neg_lo:[1,0,0] neg_hi:[1,0,0]
	v_pk_mul_f32 v[24:25], v[18:19], v[18:19]
	v_fmac_f32_e32 v41, v42, v42
	v_pk_fma_f32 v[22:23], v[122:123], v[38:39], v[36:37] neg_lo:[1,0,0] neg_hi:[1,0,0]
	v_add_f32_e32 v24, v41, v24
	v_pk_mul_f32 v[36:37], v[22:23], v[22:23]
	v_add_f32_e32 v24, v24, v25
	v_add_f32_e32 v24, v24, v36
	v_pk_mul_f32 v[38:39], v[20:21], v[20:21]
	v_add_f32_e32 v24, v24, v37
	v_add_f32_e32 v24, v24, v38
	v_add_f32_e32 v24, v24, v39
	ds_bpermute_b32 v25, v125, v24
	v_lshlrev_b32_e32 v36, 16, v10
	v_lshlrev_b32_e32 v37, 16, v14
	s_waitcnt lgkmcnt(0)
	v_add_f32_e32 v24, v24, v25
	ds_bpermute_b32 v25, v138, v24
	s_waitcnt lgkmcnt(0)
	v_add_f32_e32 v24, v24, v25
	ds_bpermute_b32 v25, v139, v24
	s_waitcnt lgkmcnt(0)
	v_add_f32_e32 v24, v24, v25
	ds_bpermute_b32 v25, v140, v24
	s_waitcnt lgkmcnt(0)
	v_add_f32_e32 v24, v24, v25
	ds_bpermute_b32 v25, v141, v24
	s_waitcnt lgkmcnt(0)
	v_add_f32_e32 v24, v24, v25
	v_fmamk_f32 v24, v24, 0x3b800000, v142
	v_mul_f32_e32 v25, 0x4b800000, v24
	v_cmp_gt_f32_e32 vcc, s53, v24
	s_nop 1
	v_cndmask_b32_e32 v24, v24, v25, vcc
	v_rsq_f32_e32 v24, v24
	s_nop 0
	v_mul_f32_e32 v25, 0x45800000, v24
	v_cndmask_b32_e32 v24, v24, v25, vcc
	v_mul_f32_e32 v24, 0x3f4ccccd, v24
	v_mul_f32_e32 v19, v19, v24
	v_mul_f32_e32 v21, v21, v24
	v_mul_f32_e32 v25, v42, v24
	v_mul_f32_e32 v38, v40, v24
	v_mul_f32_e32 v18, v18, v24
	v_mul_f32_e32 v22, v22, v24
	v_mul_f32_e32 v23, v23, v24
	v_mul_f32_e32 v20, v20, v24
	v_mul_f32_e32 v19, v203, v19
	v_mul_f32_e32 v21, v207, v21
	v_mul_f32_e32 v24, v200, v25
	v_mul_f32_e32 v25, v201, v38
	v_mul_f32_e32 v32, v202, v18
	v_mul_f32_e32 v22, v204, v22
	v_mul_f32_e32 v23, v205, v23
	v_mul_f32_e32 v28, v206, v20
	v_cvt_pk_bf16_f32 v18, v24, v25
	v_cvt_pk_bf16_f32 v19, v32, v19
	v_cvt_pk_bf16_f32 v20, v22, v23
	v_cvt_pk_bf16_f32 v21, v28, v21
	global_store_dwordx4 v[26:27], v[18:21], off offset:1024
	s_nop 1
	s_nop 0
	v_and_b32_e32 v32, 0xffff0000, v10
	v_and_b32_e32 v33, 0xffff0000, v14
	v_lshlrev_b32_e32 v10, 16, v11
	v_and_b32_e32 v11, 0xffff0000, v11
	v_lshlrev_b32_e32 v14, 16, v15
	v_and_b32_e32 v15, 0xffff0000, v15
	v_fma_f32 v32, -v122, v33, v32
	v_lshlrev_b32_e32 v28, 16, v12
	v_and_b32_e32 v29, 0xffff0000, v12
	v_lshlrev_b32_e32 v30, 16, v16
	v_and_b32_e32 v31, 0xffff0000, v16
	v_lshlrev_b32_e32 v12, 16, v13
	v_and_b32_e32 v13, 0xffff0000, v13
	v_lshlrev_b32_e32 v16, 16, v17
	v_and_b32_e32 v17, 0xffff0000, v17
	v_fma_f32 v34, -v122, v37, v36
	v_pk_fma_f32 v[10:11], v[122:123], v[14:15], v[10:11] neg_lo:[1,0,0] neg_hi:[1,0,0]
	v_mul_f32_e32 v33, v32, v32
	v_pk_fma_f32 v[12:13], v[122:123], v[16:17], v[12:13] neg_lo:[1,0,0] neg_hi:[1,0,0]
	v_pk_mul_f32 v[16:17], v[10:11], v[10:11]
	v_fmac_f32_e32 v33, v34, v34
	v_pk_fma_f32 v[14:15], v[122:123], v[30:31], v[28:29] neg_lo:[1,0,0] neg_hi:[1,0,0]
	v_add_f32_e32 v16, v33, v16
	v_pk_mul_f32 v[28:29], v[14:15], v[14:15]
	v_add_f32_e32 v16, v16, v17
	v_add_f32_e32 v16, v16, v28
	v_pk_mul_f32 v[30:31], v[12:13], v[12:13]
	v_add_f32_e32 v16, v16, v29
	v_add_f32_e32 v16, v16, v30
	v_add_f32_e32 v16, v16, v31
	ds_bpermute_b32 v17, v125, v16
	v_lshlrev_b32_e32 v28, 16, v2
	v_lshlrev_b32_e32 v29, 16, v6
	s_waitcnt lgkmcnt(0)
; __device__ __forceinline__ unsigned pk2(float lo, float hi) { return pg8::cvt_pk_bf16(lo, hi); }
; __device__ __forceinline__ float bf_lo(unsigned w) { return __uint_as_float(w << 16); }
; __device__ __forceinline__ float bf_hi(unsigned w) { return __uint_as_float(w & 0xffff0000u); }
; __global__ void __launch_bounds__(512, 2) fwd_mega(Params P_by_kernarg) {
;     ...
;             for (int q = 0; q < 4; ++q) { const int rq = row + q * NGW; if (rq < MX) {
; #pragma unroll
;             for (int j = 0; j < 4; ++j) { const int col = (lane + 64 * j) * 8;
;                 const u32x4 a = av[q][j], bq = bv[q][j];
;                 float d[8]; d[0] = bf_lo(a.x) - lam * bf_lo(bq.x); d[1] = bf_hi(a.x) - lam * bf_hi(bq.x); d[2] = bf_lo(a.y) - lam * bf_lo(bq.y); d[3] = bf_hi(a.y) - lam * bf_hi(bq.y);
;                 d[4] = bf_lo(a.z) - lam * bf_lo(bq.z); d[5] = bf_hi(a.z) - lam * bf_hi(bq.z); d[6] = bf_lo(a.w) - lam * bf_lo(bq.w); d[7] = bf_hi(a.w) - lam * bf_hi(bq.w);
;                 float ss = 0.f;
; #pragma unroll
;                 for (int e = 0; e < 8; ++e) ss += d[e] * d[e];
;                 ss += __shfl_xor(ss, 1); ss += __shfl_xor(ss, 2); ss += __shfl_xor(ss, 4); ss += __shfl_xor(ss, 8); ss += __shfl_xor(ss, 16);
;                 const float rs = rsqrtf(ss * (1.f / 256.f) + EPS) * 0.8f;
;                 const f32x4 g0 = *(const f32x4*)(KA->in[8] + (col & 255)), g1 = *(const f32x4*)(KA->in[8] + (col & 255) + 4);
;                 u32x4 w; w.x = pk2(d[0] * rs * g0[0], d[1] * rs * g0[1]); w.y = pk2(d[2] * rs * g0[2], d[3] * rs * g0[3]); w.z = pk2(d[4] * rs * g1[0], d[5] * rs * g1[1]); w.w = pk2(d[6] * rs * g1[2], d[7] * rs * g1[3]);
;                 *(u32x4*)(Cat + (size_t)rq * DM + col) = w; } } }
	v_add_f32_e32 v16, v16, v17
	ds_bpermute_b32 v17, v138, v16
	s_waitcnt lgkmcnt(0)
	v_add_f32_e32 v16, v16, v17
	ds_bpermute_b32 v17, v139, v16
	s_waitcnt lgkmcnt(0)
	v_add_f32_e32 v16, v16, v17
	ds_bpermute_b32 v17, v140, v16
	s_waitcnt lgkmcnt(0)
	v_add_f32_e32 v16, v16, v17
	ds_bpermute_b32 v17, v141, v16
	s_waitcnt lgkmcnt(0)
	v_add_f32_e32 v16, v16, v17
	v_fmamk_f32 v16, v16, 0x3b800000, v142
	v_mul_f32_e32 v17, 0x4b800000, v16
	v_cmp_gt_f32_e32 vcc, s53, v16
	s_nop 1
	v_cndmask_b32_e32 v16, v16, v17, vcc
	v_rsq_f32_e32 v16, v16
	s_nop 0
	v_mul_f32_e32 v17, 0x45800000, v16
	v_cndmask_b32_e32 v16, v16, v17, vcc
	v_mul_f32_e32 v16, 0x3f4ccccd, v16
	v_mul_f32_e32 v11, v11, v16
	v_mul_f32_e32 v13, v13, v16
	v_mul_f32_e32 v17, v34, v16
	v_mul_f32_e32 v30, v32, v16
	v_mul_f32_e32 v10, v10, v16
	v_mul_f32_e32 v14, v14, v16
	v_mul_f32_e32 v15, v15, v16
	v_mul_f32_e32 v12, v12, v16
	v_mul_f32_e32 v11, v203, v11
	v_mul_f32_e32 v13, v207, v13
	v_mul_f32_e32 v16, v200, v17
	v_mul_f32_e32 v17, v201, v30
	v_mul_f32_e32 v22, v202, v10
	v_mul_f32_e32 v14, v204, v14
	v_mul_f32_e32 v15, v205, v15
	v_mul_f32_e32 v18, v206, v12
	v_cvt_pk_bf16_f32 v10, v16, v17
	v_cvt_pk_bf16_f32 v11, v22, v11
	v_cvt_pk_bf16_f32 v12, v14, v15
	v_cvt_pk_bf16_f32 v13, v18, v13
	global_store_dwordx4 v[26:27], v[10:13], off offset:2048
	s_nop 1
	s_nop 0
	v_and_b32_e32 v22, 0xffff0000, v2
	v_and_b32_e32 v23, 0xffff0000, v6
	v_lshlrev_b32_e32 v2, 16, v3
	v_and_b32_e32 v3, 0xffff0000, v3
	v_lshlrev_b32_e32 v6, 16, v7
	v_and_b32_e32 v7, 0xffff0000, v7
	v_fma_f32 v22, -v122, v23, v22
	v_lshlrev_b32_e32 v18, 16, v4
	v_and_b32_e32 v19, 0xffff0000, v4
	v_lshlrev_b32_e32 v20, 16, v8
	v_and_b32_e32 v21, 0xffff0000, v8
	v_lshlrev_b32_e32 v4, 16, v5
	v_and_b32_e32 v5, 0xffff0000, v5
	v_lshlrev_b32_e32 v8, 16, v9
	v_and_b32_e32 v9, 0xffff0000, v9
	v_fma_f32 v24, -v122, v29, v28
	v_pk_fma_f32 v[2:3], v[122:123], v[6:7], v[2:3] neg_lo:[1,0,0] neg_hi:[1,0,0]
	v_mul_f32_e32 v23, v22, v22
	v_pk_fma_f32 v[4:5], v[122:123], v[8:9], v[4:5] neg_lo:[1,0,0] neg_hi:[1,0,0]
	v_pk_mul_f32 v[8:9], v[2:3], v[2:3]
	v_fmac_f32_e32 v23, v24, v24
	v_pk_fma_f32 v[6:7], v[122:123], v[20:21], v[18:19] neg_lo:[1,0,0] neg_hi:[1,0,0]
	v_add_f32_e32 v8, v23, v8
	v_pk_mul_f32 v[18:19], v[6:7], v[6:7]
	v_add_f32_e32 v8, v8, v9
	v_add_f32_e32 v8, v8, v18
	v_pk_mul_f32 v[20:21], v[4:5], v[4:5]
	v_add_f32_e32 v8, v8, v19
	v_add_f32_e32 v8, v8, v20
	v_add_f32_e32 v8, v8, v21
	ds_bpermute_b32 v9, v125, v8
	s_waitcnt lgkmcnt(0)
	v_add_f32_e32 v8, v8, v9
	ds_bpermute_b32 v9, v138, v8
	s_waitcnt lgkmcnt(0)
	v_add_f32_e32 v8, v8, v9
	ds_bpermute_b32 v9, v139, v8
	s_waitcnt lgkmcnt(0)
	v_add_f32_e32 v8, v8, v9
	ds_bpermute_b32 v9, v140, v8
	s_waitcnt lgkmcnt(0)
	v_add_f32_e32 v8, v8, v9
	ds_bpermute_b32 v9, v141, v8
	s_waitcnt lgkmcnt(0)
	v_add_f32_e32 v8, v8, v9
	v_fmamk_f32 v8, v8, 0x3b800000, v142
	v_mul_f32_e32 v9, 0x4b800000, v8
	v_cmp_gt_f32_e32 vcc, s53, v8
	s_nop 1
	v_cndmask_b32_e32 v8, v8, v9, vcc
	v_rsq_f32_e32 v8, v8
	s_nop 0
	v_mul_f32_e32 v9, 0x45800000, v8
	v_cndmask_b32_e32 v8, v8, v9, vcc
	v_mul_f32_e32 v8, 0x3f4ccccd, v8
	v_mul_f32_e32 v3, v3, v8
	v_mul_f32_e32 v5, v5, v8
	v_mul_f32_e32 v9, v24, v8
	v_mul_f32_e32 v18, v22, v8
	v_mul_f32_e32 v2, v2, v8
	v_mul_f32_e32 v6, v6, v8
	v_mul_f32_e32 v7, v7, v8
	v_mul_f32_e32 v4, v4, v8
	v_mul_f32_e32 v3, v203, v3
	v_mul_f32_e32 v5, v207, v5
	v_mul_f32_e32 v8, v200, v9
	v_mul_f32_e32 v9, v201, v18
	v_mul_f32_e32 v14, v202, v2
	v_mul_f32_e32 v6, v204, v6
	v_mul_f32_e32 v7, v205, v7
	v_mul_f32_e32 v10, v206, v4
	v_cvt_pk_bf16_f32 v2, v8, v9
	v_cvt_pk_bf16_f32 v3, v14, v3
	v_cvt_pk_bf16_f32 v4, v6, v7
	v_cvt_pk_bf16_f32 v5, v10, v5
	global_store_dwordx4 v[26:27], v[2:5], off offset:3072
	s_branch .LBB0_610
